# aligned combo12 + dead re-staging loads of the last unit's last K-iteration made uniform-address in UP and IN as well (UP: first-segment loads kept live)
# baseline (speedup 1.0000x reference)
; #define PG8_STAGE(bufoff, gbase, voff) do { _Pragma("unroll") for (int _i = 0; _i < 2; ++_i) \
;         __builtin_amdgcn_global_load_lds((const unsigned*)((const char*)(gbase) + (voff)[_i]), (PG8_LAS unsigned*)(lds + (bufoff) + ldsw + _i * 8192), 16, 0, 0); } while (0)
; #define PG8_LDA(dst, b, h) do { _Pragma("unroll") for (int m = 0; m < 4; ++m) _Pragma("unroll") for (int k = 0; k < 2; ++k) dst[m][k] = *(const PG8_LAS bf16x8*)(lds + PG8_SA(b, h) + aoff + m * 2048 + k * 1024); } while (0)
; #define PG8_LDB(dst, b, h) do { _Pragma("unroll") for (int n = 0; n < 2; ++n) _Pragma("unroll") for (int k = 0; k < 2; ++k) dst[n][k] = *(const PG8_LAS bf16x8*)(lds + PG8_SB(b, h) + boff + n * 2048 + k * 1024); } while (0)
; #define PG8_MMA(ai, bj, At, Bt) do { __builtin_amdgcn_s_setprio(1); _Pragma("unroll") for (int m = 0; m < 4; ++m) _Pragma("unroll") for (int n = 0; n < 2; ++n) _Pragma("unroll") for (int k = 0; k < 2; ++k) \
;         acc[ai][bj][m][n] = __builtin_amdgcn_mfma_f32_16x16x32_bf16(Bt[n][k], At[m][k], acc[ai][bj][m][n], 0, 0, 0); __builtin_amdgcn_s_setprio(0); } while (0)
; #define PG8_WAIT_V(n) asm volatile("s_waitcnt vmcnt(" #n ")" ::: "memory")
; #define PG8_WAIT_L(n) asm volatile("s_waitcnt lgkmcnt(" #n ")" ::: "memory")
; #define PG8_BAR __builtin_amdgcn_s_barrier()
; #define PG8_SCHED __builtin_amdgcn_sched_barrier(0)
; template <class Epi, class Sched, bool ALIGN_EPI = false, bool SP2 = false, bool ACHUNK = false>
; __device__ __forceinline__ void gemm_phase(PG8_LAS unsigned char* lds, const Gemm g, const Sched& S, const Epi& E) {
;     ...
;             if constexpr (SP2) {
;             PG8_LDB(B0, 0, 0); PG8_LDB(B1, 0, 1); PG8_SCHED; PG8_LDA(At, 0, 0); PG8_STAGE(PG8_SA(1, 1), a1 + hstepA, voffA);
;             PG8_WAIT_V(8); PG8_WAIT_L(0); PG8_BAR; PG8_MMA(0, 0, At, B0); PG8_MMA(0, 1, At, B1); PG8_BAR; PG8_SCHED;
;             PG8_LDA(At, 0, 1); PG8_STAGE(PG8_SB(0, 0), b2, voffB); PG8_STAGE(PG8_SB(0, 1), b2 + hstepB, voffB); PG8_STAGE(PG8_SA(0, 0), a2, voffA);
;             PG8_WAIT_V(8); PG8_WAIT_L(0); PG8_BAR; PG8_MMA(1, 0, At, B0); PG8_MMA(1, 1, At, B1); PG8_BAR; PG8_SCHED;
.LBB0_106:
	s_andn2_b64 vcc, exec, s[44:45]
	s_nop 0
	s_cbranch_vccnz .LBB0_110
	s_add_u32 s8, s4, 0x100
	s_addc_u32 s9, s5, 0
	s_add_u32 s0, s6, 0x80
	s_addc_u32 s1, s7, 0
	s_mov_b32 s4, 0
	s_add_i32 s6, s4, 2
	s_add_u32 s7, s0, 0x80
	s_addc_u32 s5, s1, 0
	s_add_i32 s77, 0, 0x10000
	s_cmp_eq_u32 s54, s4
	s_cselect_b32 s5, s49, s5
	s_cselect_b32 s4, s48, s7
	v_add_u32_e32 v2, s77, v224
	s_cselect_b32 s79, s51, s9
	s_cselect_b32 s78, s50, s8
	s_mov_b32 vcc_lo, 0
	s_cbranch_scc0 .Lnl_up_pe
	s_cmpk_lg_u32 s87, 0x100
	s_cbranch_scc1 .Lnl_up_pe
	s_cmp_eq_u32 s40, 0
	s_cbranch_scc1 .Lnl_up_pe
	v_mov_b32_e32 v174, 0
	v_mov_b32_e32 v178, 0
	s_mov_b32 vcc_lo, 1
.Lnl_up_pe:
	s_add_i32 s7, 0, 0x14000
	s_waitcnt lgkmcnt(0)
	ds_read_b128 v[36:39], v2
	ds_read_b128 v[40:43], v2 offset:1024
	ds_read_b128 v[44:47], v2 offset:2048
	ds_read_b128 v[48:51], v2 offset:3072
	v_add_u32_e32 v2, s7, v224
	ds_read_b128 v[52:55], v2
	ds_read_b128 v[56:59], v2 offset:1024
	ds_read_b128 v[60:63], v2 offset:2048
	ds_read_b128 v[64:67], v2 offset:3072
	s_add_u32 s98, s0, s28
	s_addc_u32 s99, s1, s29
	s_add_i32 m0, s25, 0xc000
	ds_read_b128 v[164:167], v238
	ds_read_b128 v[168:171], v238 offset:1024
	ds_read_b128 v[184:187], v238 offset:2048
	ds_read_b128 v[188:191], v238 offset:3072
	ds_read_b128 v[198:201], v238 offset:4096
	ds_read_b128 v[202:205], v238 offset:5120
	ds_read_b128 v[206:209], v238 offset:6144
	ds_read_b128 v[210:213], v238 offset:7168
	global_load_lds_dwordx4 v172, s[98:99]
	s_add_i32 m0, s25, 0xe000
	s_nop 0
	global_load_lds_dwordx4 v176, s[98:99]
	s_waitcnt vmcnt(8)
	s_waitcnt lgkmcnt(0)
	s_barrier
	s_setprio 1
	v_mfma_f32_16x16x32_bf16 v[148:151], v[36:39], v[164:167], 0
	v_mfma_f32_16x16x32_bf16 v[152:155], v[44:47], v[164:167], 0
	v_mfma_f32_16x16x32_bf16 v[132:135], v[36:39], v[184:187], 0
	v_mfma_f32_16x16x32_bf16 v[140:143], v[44:47], v[184:187], 0
	v_mfma_f32_16x16x32_bf16 v[136:139], v[36:39], v[198:201], 0
	v_mfma_f32_16x16x32_bf16 v[144:147], v[44:47], v[198:201], 0
	v_mfma_f32_16x16x32_bf16 v[160:163], v[36:39], v[206:209], 0
	v_mfma_f32_16x16x32_bf16 v[156:159], v[44:47], v[206:209], 0
	v_mfma_f32_16x16x32_bf16 v[148:151], v[40:43], v[168:171], v[148:151]
	v_mfma_f32_16x16x32_bf16 v[152:155], v[48:51], v[168:171], v[152:155]
	v_mfma_f32_16x16x32_bf16 v[132:135], v[40:43], v[188:191], v[132:135]
	v_mfma_f32_16x16x32_bf16 v[140:143], v[48:51], v[188:191], v[140:143]
	v_mfma_f32_16x16x32_bf16 v[136:139], v[40:43], v[202:205], v[136:139]
	v_mfma_f32_16x16x32_bf16 v[144:147], v[48:51], v[202:205], v[144:147]
	v_mfma_f32_16x16x32_bf16 v[160:163], v[40:43], v[210:213], v[160:163]
	v_mfma_f32_16x16x32_bf16 v[156:159], v[48:51], v[210:213], v[156:159]
	s_setprio 0
	s_setprio 1
	v_mfma_f32_16x16x32_bf16 v[124:127], v[52:55], v[164:167], 0
	v_mfma_f32_16x16x32_bf16 v[128:131], v[60:63], v[164:167], 0
	v_mfma_f32_16x16x32_bf16 v[116:119], v[52:55], v[184:187], 0
	v_mfma_f32_16x16x32_bf16 v[120:123], v[60:63], v[184:187], 0
	v_mfma_f32_16x16x32_bf16 v[112:115], v[52:55], v[198:201], 0
	v_mfma_f32_16x16x32_bf16 v[108:111], v[60:63], v[198:201], 0
	v_mfma_f32_16x16x32_bf16 v[104:107], v[52:55], v[206:209], 0
	v_mfma_f32_16x16x32_bf16 v[100:103], v[60:63], v[206:209], 0
	v_mfma_f32_16x16x32_bf16 v[124:127], v[56:59], v[168:171], v[124:127]
	v_mfma_f32_16x16x32_bf16 v[128:131], v[64:67], v[168:171], v[128:131]
	v_mfma_f32_16x16x32_bf16 v[116:119], v[56:59], v[188:191], v[116:119]
	v_mfma_f32_16x16x32_bf16 v[120:123], v[64:67], v[188:191], v[120:123]
	v_mfma_f32_16x16x32_bf16 v[112:115], v[56:59], v[202:205], v[112:115]
	v_mfma_f32_16x16x32_bf16 v[108:111], v[64:67], v[202:205], v[108:111]
	v_mfma_f32_16x16x32_bf16 v[104:107], v[56:59], v[210:213], v[104:107]
	v_mfma_f32_16x16x32_bf16 v[100:103], v[64:67], v[210:213], v[100:103]
	s_setprio 0
	s_barrier
	s_add_i32 s77, s77, s17
	s_add_u32 s98, s78, s18
	s_addc_u32 s99, s79, s19
	s_mov_b32 m0, s77
	ds_read_b128 v[164:167], v238 offset:16384
	ds_read_b128 v[168:171], v238 offset:17408
	ds_read_b128 v[184:187], v238 offset:18432
	ds_read_b128 v[188:191], v238 offset:19456
	ds_read_b128 v[198:201], v238 offset:20480
	ds_read_b128 v[202:205], v238 offset:21504
	ds_read_b128 v[206:209], v238 offset:22528
	ds_read_b128 v[210:213], v238 offset:23552
	global_load_lds_dwordx4 v174, s[78:79]
	s_add_i32 m0, s77, 0x2000
	s_add_i32 s7, s7, s17
	global_load_lds_dwordx4 v178, s[78:79]
	s_mov_b32 m0, s7
	s_nop 0
	global_load_lds_dwordx4 v174, s[98:99]
	s_add_i32 m0, s7, 0x2000
	s_nop 0
	global_load_lds_dwordx4 v178, s[98:99]
	s_cmp_eq_u32 vcc_lo, 0
	s_cbranch_scc1 .Lnl_up2_pe
	v_mov_b32_e32 v172, 0
	v_mov_b32_e32 v176, 0
; #define PG8_STAGE(bufoff, gbase, voff) do { _Pragma("unroll") for (int _i = 0; _i < 2; ++_i) \
;         __builtin_amdgcn_global_load_lds((const unsigned*)((const char*)(gbase) + (voff)[_i]), (PG8_LAS unsigned*)(lds + (bufoff) + ldsw + _i * 8192), 16, 0, 0); } while (0)
; #define PG8_LDA(dst, b, h) do { _Pragma("unroll") for (int m = 0; m < 4; ++m) _Pragma("unroll") for (int k = 0; k < 2; ++k) dst[m][k] = *(const PG8_LAS bf16x8*)(lds + PG8_SA(b, h) + aoff + m * 2048 + k * 1024); } while (0)
; #define PG8_LDB(dst, b, h) do { _Pragma("unroll") for (int n = 0; n < 2; ++n) _Pragma("unroll") for (int k = 0; k < 2; ++k) dst[n][k] = *(const PG8_LAS bf16x8*)(lds + PG8_SB(b, h) + boff + n * 2048 + k * 1024); } while (0)
; #define PG8_MMA(ai, bj, At, Bt) do { __builtin_amdgcn_s_setprio(1); _Pragma("unroll") for (int m = 0; m < 4; ++m) _Pragma("unroll") for (int n = 0; n < 2; ++n) _Pragma("unroll") for (int k = 0; k < 2; ++k) \
;         acc[ai][bj][m][n] = __builtin_amdgcn_mfma_f32_16x16x32_bf16(Bt[n][k], At[m][k], acc[ai][bj][m][n], 0, 0, 0); __builtin_amdgcn_s_setprio(0); } while (0)
; #define PG8_WAIT_V(n) asm volatile("s_waitcnt vmcnt(" #n ")" ::: "memory")
; #define PG8_WAIT_L(n) asm volatile("s_waitcnt lgkmcnt(" #n ")" ::: "memory")
; #define PG8_BAR __builtin_amdgcn_s_barrier()
; #define PG8_SCHED __builtin_amdgcn_sched_barrier(0)
; template <class Epi, class Sched, bool ALIGN_EPI = false, bool SP2 = false, bool ACHUNK = false>
; __device__ __forceinline__ void gemm_phase(PG8_LAS unsigned char* lds, const Gemm g, const Sched& S, const Epi& E) {
;     ...
;             PG8_LDB(B0, 0, 0); PG8_LDB(B1, 0, 1); PG8_SCHED; PG8_LDA(At, 0, 0); PG8_STAGE(PG8_SA(1, 1), a1 + hstepA, voffA);
;             PG8_WAIT_V(8); PG8_WAIT_L(0); PG8_BAR; PG8_MMA(0, 0, At, B0); PG8_MMA(0, 1, At, B1); PG8_BAR; PG8_SCHED;
;             PG8_LDA(At, 0, 1); PG8_STAGE(PG8_SB(0, 0), b2, voffB); PG8_STAGE(PG8_SB(0, 1), b2 + hstepB, voffB); PG8_STAGE(PG8_SA(0, 0), a2, voffA);
;             PG8_WAIT_V(8); PG8_WAIT_L(0); PG8_BAR; PG8_MMA(1, 0, At, B0); PG8_MMA(1, 1, At, B1); PG8_BAR; PG8_SCHED;
.Lnl_up2_pe:
	s_mov_b32 m0, s25
	s_nop 0
	global_load_lds_dwordx4 v172, s[4:5]
	s_mov_b32 m0, s26
	s_nop 0
	global_load_lds_dwordx4 v176, s[4:5]
	s_waitcnt vmcnt(8)
	s_waitcnt lgkmcnt(0)
	s_barrier
	s_setprio 1
	v_mfma_f32_16x16x32_bf16 v[96:99], v[36:39], v[164:167], 0
	v_mfma_f32_16x16x32_bf16 v[92:95], v[44:47], v[164:167], 0
	v_mfma_f32_16x16x32_bf16 v[88:91], v[36:39], v[184:187], 0
	v_mfma_f32_16x16x32_bf16 v[84:87], v[44:47], v[184:187], 0
	v_mfma_f32_16x16x32_bf16 v[80:83], v[36:39], v[198:201], 0
	v_mfma_f32_16x16x32_bf16 v[76:79], v[44:47], v[198:201], 0
	v_mfma_f32_16x16x32_bf16 v[36:39], v[36:39], v[206:209], 0
	v_mfma_f32_16x16x32_bf16 v[96:99], v[40:43], v[168:171], v[96:99]
	v_mfma_f32_16x16x32_bf16 v[92:95], v[48:51], v[168:171], v[92:95]
	v_mfma_f32_16x16x32_bf16 v[88:91], v[40:43], v[188:191], v[88:91]
	v_mfma_f32_16x16x32_bf16 v[84:87], v[48:51], v[188:191], v[84:87]
	v_mfma_f32_16x16x32_bf16 v[80:83], v[40:43], v[202:205], v[80:83]
	v_mfma_f32_16x16x32_bf16 v[76:79], v[48:51], v[202:205], v[76:79]
	v_mfma_f32_16x16x32_bf16 v[36:39], v[40:43], v[210:213], v[36:39]
	v_mfma_f32_16x16x32_bf16 v[40:43], v[44:47], v[206:209], 0
	v_mfma_f32_16x16x32_bf16 v[40:43], v[48:51], v[210:213], v[40:43]
	s_setprio 0
	s_setprio 1
	v_mfma_f32_16x16x32_bf16 v[28:31], v[52:55], v[164:167], 0
	v_mfma_f32_16x16x32_bf16 v[32:35], v[60:63], v[164:167], 0
	v_mfma_f32_16x16x32_bf16 v[20:23], v[52:55], v[184:187], 0
	v_mfma_f32_16x16x32_bf16 v[24:27], v[60:63], v[184:187], 0
	v_mfma_f32_16x16x32_bf16 v[16:19], v[52:55], v[198:201], 0
	v_mfma_f32_16x16x32_bf16 v[12:15], v[60:63], v[198:201], 0
	v_mfma_f32_16x16x32_bf16 v[8:11], v[52:55], v[206:209], 0
	v_mfma_f32_16x16x32_bf16 v[4:7], v[60:63], v[206:209], 0
	v_mfma_f32_16x16x32_bf16 v[28:31], v[56:59], v[168:171], v[28:31]
	v_mfma_f32_16x16x32_bf16 v[32:35], v[64:67], v[168:171], v[32:35]
	v_mfma_f32_16x16x32_bf16 v[20:23], v[56:59], v[188:191], v[20:23]
	v_mfma_f32_16x16x32_bf16 v[24:27], v[64:67], v[188:191], v[24:27]
	v_mfma_f32_16x16x32_bf16 v[16:19], v[56:59], v[202:205], v[16:19]
	v_mfma_f32_16x16x32_bf16 v[12:15], v[64:67], v[202:205], v[12:15]
	v_mfma_f32_16x16x32_bf16 v[8:11], v[56:59], v[210:213], v[8:11]
	v_mfma_f32_16x16x32_bf16 v[4:7], v[64:67], v[210:213], v[4:7]
	s_setprio 0
	s_barrier
	s_branch .Lpe_join_108
	.p2align	6
.LBB0_108:
	s_add_i32 s6, s4, 2
	s_add_u32 s7, s0, 0x80
	s_addc_u32 s5, s1, 0
	s_add_i32 s77, 0, 0x10000
	s_cmp_eq_u32 s54, s4
	s_cselect_b32 s5, s49, s5
	s_cselect_b32 s4, s48, s7
	v_add_u32_e32 v2, s77, v224
	s_cselect_b32 s79, s51, s9
	s_cselect_b32 s78, s50, s8
	s_mov_b32 vcc_lo, 0
	s_cbranch_scc0 .Lnl_up
	s_cmpk_lg_u32 s87, 0x100
	s_cbranch_scc1 .Lnl_up
	s_cmp_eq_u32 s40, 0
	s_cbranch_scc1 .Lnl_up
	v_mov_b32_e32 v174, 0
	v_mov_b32_e32 v178, 0
	s_mov_b32 vcc_lo, 1
; #define PG8_STAGE(bufoff, gbase, voff) do { _Pragma("unroll") for (int _i = 0; _i < 2; ++_i) \
;         __builtin_amdgcn_global_load_lds((const unsigned*)((const char*)(gbase) + (voff)[_i]), (PG8_LAS unsigned*)(lds + (bufoff) + ldsw + _i * 8192), 16, 0, 0); } while (0)
; #define PG8_LDA(dst, b, h) do { _Pragma("unroll") for (int m = 0; m < 4; ++m) _Pragma("unroll") for (int k = 0; k < 2; ++k) dst[m][k] = *(const PG8_LAS bf16x8*)(lds + PG8_SA(b, h) + aoff + m * 2048 + k * 1024); } while (0)
; #define PG8_LDB(dst, b, h) do { _Pragma("unroll") for (int n = 0; n < 2; ++n) _Pragma("unroll") for (int k = 0; k < 2; ++k) dst[n][k] = *(const PG8_LAS bf16x8*)(lds + PG8_SB(b, h) + boff + n * 2048 + k * 1024); } while (0)
; #define PG8_MMA(ai, bj, At, Bt) do { __builtin_amdgcn_s_setprio(1); _Pragma("unroll") for (int m = 0; m < 4; ++m) _Pragma("unroll") for (int n = 0; n < 2; ++n) _Pragma("unroll") for (int k = 0; k < 2; ++k) \
;         acc[ai][bj][m][n] = __builtin_amdgcn_mfma_f32_16x16x32_bf16(Bt[n][k], At[m][k], acc[ai][bj][m][n], 0, 0, 0); __builtin_amdgcn_s_setprio(0); } while (0)
; template <class Epi, class Sched, bool ALIGN_EPI = false, bool SP2 = false, bool ACHUNK = false>
; __device__ __forceinline__ void gemm_phase(PG8_LAS unsigned char* lds, const Gemm g, const Sched& S, const Epi& E) {
;     ...
;             if constexpr (SP2) {
;             PG8_LDB(B0, 0, 0); PG8_LDB(B1, 0, 1); PG8_SCHED; PG8_LDA(At, 0, 0); PG8_STAGE(PG8_SA(1, 1), a1 + hstepA, voffA);
;             PG8_WAIT_V(8); PG8_WAIT_L(0); PG8_BAR; PG8_MMA(0, 0, At, B0); PG8_MMA(0, 1, At, B1); PG8_BAR; PG8_SCHED;
;             PG8_LDA(At, 0, 1); PG8_STAGE(PG8_SB(0, 0), b2, voffB); PG8_STAGE(PG8_SB(0, 1), b2 + hstepB, voffB); PG8_STAGE(PG8_SA(0, 0), a2, voffA);
;             PG8_WAIT_V(8); PG8_WAIT_L(0); PG8_BAR; PG8_MMA(1, 0, At, B0); PG8_MMA(1, 1, At, B1); PG8_BAR; PG8_SCHED;
;             PG8_LDB(B0, 1, 0); PG8_LDB(B1, 1, 1); PG8_SCHED; PG8_LDA(At, 1, 0); PG8_STAGE(PG8_SA(0, 1), a2 + hstepA, voffA);
;             PG8_WAIT_V(8); PG8_WAIT_L(0); PG8_BAR; PG8_MMA(0, 0, At, B0); PG8_MMA(0, 1, At, B1); PG8_BAR; PG8_SCHED;
;             PG8_LDA(At, 1, 1); PG8_STAGE(PG8_SB(1, 0), b3, voffB); PG8_STAGE(PG8_SB(1, 1), b3 + hstepB, voffB); PG8_STAGE(PG8_SA(1, 0), a3, voffA);
;             PG8_WAIT_V(8); PG8_WAIT_L(0); PG8_BAR; PG8_MMA(1, 0, At, B0); PG8_MMA(1, 1, At, B1); PG8_BAR; PG8_SCHED;
.Lnl_up:
	s_add_i32 s7, 0, 0x14000
	s_waitcnt lgkmcnt(0)
	ds_read_b128 v[36:39], v2
	ds_read_b128 v[40:43], v2 offset:1024
	ds_read_b128 v[44:47], v2 offset:2048
	ds_read_b128 v[48:51], v2 offset:3072
	v_add_u32_e32 v2, s7, v224
	ds_read_b128 v[52:55], v2
	ds_read_b128 v[56:59], v2 offset:1024
	ds_read_b128 v[60:63], v2 offset:2048
	ds_read_b128 v[64:67], v2 offset:3072
	s_add_u32 s98, s0, s28
	s_addc_u32 s99, s1, s29
	s_add_i32 m0, s25, 0xc000
	ds_read_b128 v[164:167], v238
	ds_read_b128 v[168:171], v238 offset:1024
	ds_read_b128 v[184:187], v238 offset:2048
	ds_read_b128 v[188:191], v238 offset:3072
	ds_read_b128 v[198:201], v238 offset:4096
	ds_read_b128 v[202:205], v238 offset:5120
	ds_read_b128 v[206:209], v238 offset:6144
	ds_read_b128 v[210:213], v238 offset:7168
	global_load_lds_dwordx4 v172, s[98:99]
	s_add_i32 m0, s25, 0xe000
	s_nop 0
	global_load_lds_dwordx4 v176, s[98:99]
	s_waitcnt vmcnt(8)
	s_waitcnt lgkmcnt(0)
	s_barrier
	s_setprio 1
	v_mfma_f32_16x16x32_bf16 v[148:151], v[36:39], v[164:167], v[148:151]
	v_mfma_f32_16x16x32_bf16 v[152:155], v[44:47], v[164:167], v[152:155]
	v_mfma_f32_16x16x32_bf16 v[132:135], v[36:39], v[184:187], v[132:135]
	v_mfma_f32_16x16x32_bf16 v[140:143], v[44:47], v[184:187], v[140:143]
	v_mfma_f32_16x16x32_bf16 v[136:139], v[36:39], v[198:201], v[136:139]
	v_mfma_f32_16x16x32_bf16 v[144:147], v[44:47], v[198:201], v[144:147]
	v_mfma_f32_16x16x32_bf16 v[160:163], v[36:39], v[206:209], v[160:163]
	v_mfma_f32_16x16x32_bf16 v[156:159], v[44:47], v[206:209], v[156:159]
	v_mfma_f32_16x16x32_bf16 v[148:151], v[40:43], v[168:171], v[148:151]
	v_mfma_f32_16x16x32_bf16 v[152:155], v[48:51], v[168:171], v[152:155]
	v_mfma_f32_16x16x32_bf16 v[132:135], v[40:43], v[188:191], v[132:135]
	v_mfma_f32_16x16x32_bf16 v[140:143], v[48:51], v[188:191], v[140:143]
	v_mfma_f32_16x16x32_bf16 v[136:139], v[40:43], v[202:205], v[136:139]
	v_mfma_f32_16x16x32_bf16 v[144:147], v[48:51], v[202:205], v[144:147]
	v_mfma_f32_16x16x32_bf16 v[160:163], v[40:43], v[210:213], v[160:163]
	v_mfma_f32_16x16x32_bf16 v[156:159], v[48:51], v[210:213], v[156:159]
	s_setprio 0
	s_setprio 1
	v_mfma_f32_16x16x32_bf16 v[124:127], v[52:55], v[164:167], v[124:127]
	v_mfma_f32_16x16x32_bf16 v[128:131], v[60:63], v[164:167], v[128:131]
	v_mfma_f32_16x16x32_bf16 v[116:119], v[52:55], v[184:187], v[116:119]
	v_mfma_f32_16x16x32_bf16 v[120:123], v[60:63], v[184:187], v[120:123]
	v_mfma_f32_16x16x32_bf16 v[112:115], v[52:55], v[198:201], v[112:115]
	v_mfma_f32_16x16x32_bf16 v[108:111], v[60:63], v[198:201], v[108:111]
	v_mfma_f32_16x16x32_bf16 v[104:107], v[52:55], v[206:209], v[104:107]
	v_mfma_f32_16x16x32_bf16 v[100:103], v[60:63], v[206:209], v[100:103]
	v_mfma_f32_16x16x32_bf16 v[124:127], v[56:59], v[168:171], v[124:127]
	v_mfma_f32_16x16x32_bf16 v[128:131], v[64:67], v[168:171], v[128:131]
	v_mfma_f32_16x16x32_bf16 v[116:119], v[56:59], v[188:191], v[116:119]
	v_mfma_f32_16x16x32_bf16 v[120:123], v[64:67], v[188:191], v[120:123]
	v_mfma_f32_16x16x32_bf16 v[112:115], v[56:59], v[202:205], v[112:115]
	v_mfma_f32_16x16x32_bf16 v[108:111], v[64:67], v[202:205], v[108:111]
	v_mfma_f32_16x16x32_bf16 v[104:107], v[56:59], v[210:213], v[104:107]
	v_mfma_f32_16x16x32_bf16 v[100:103], v[64:67], v[210:213], v[100:103]
	s_setprio 0
	s_barrier
	s_add_i32 s77, s77, s17
	s_add_u32 s98, s78, s18
	s_addc_u32 s99, s79, s19
	s_mov_b32 m0, s77
	ds_read_b128 v[164:167], v238 offset:16384
	ds_read_b128 v[168:171], v238 offset:17408
	ds_read_b128 v[184:187], v238 offset:18432
	ds_read_b128 v[188:191], v238 offset:19456
	ds_read_b128 v[198:201], v238 offset:20480
	ds_read_b128 v[202:205], v238 offset:21504
	ds_read_b128 v[206:209], v238 offset:22528
	ds_read_b128 v[210:213], v238 offset:23552
	global_load_lds_dwordx4 v174, s[78:79]
	s_add_i32 m0, s77, 0x2000
	s_add_i32 s7, s7, s17
	global_load_lds_dwordx4 v178, s[78:79]
	s_mov_b32 m0, s7
	s_nop 0
	global_load_lds_dwordx4 v174, s[98:99]
	s_add_i32 m0, s7, 0x2000
	s_nop 0
	global_load_lds_dwordx4 v178, s[98:99]
	s_cmp_eq_u32 vcc_lo, 0
	s_cbranch_scc1 .Lnl_up2
	v_mov_b32_e32 v172, 0
	v_mov_b32_e32 v176, 0
.Lnl_up2:
	s_mov_b32 m0, s25
	s_nop 0
	global_load_lds_dwordx4 v172, s[4:5]
	s_mov_b32 m0, s26
	s_nop 0
	global_load_lds_dwordx4 v176, s[4:5]
	s_waitcnt vmcnt(8)
	s_waitcnt lgkmcnt(0)
	s_barrier
	s_setprio 1
	v_mfma_f32_16x16x32_bf16 v[96:99], v[36:39], v[164:167], v[96:99]
	v_mfma_f32_16x16x32_bf16 v[92:95], v[44:47], v[164:167], v[92:95]
	v_mfma_f32_16x16x32_bf16 v[88:91], v[36:39], v[184:187], v[88:91]
	v_mfma_f32_16x16x32_bf16 v[84:87], v[44:47], v[184:187], v[84:87]
	v_mfma_f32_16x16x32_bf16 v[80:83], v[36:39], v[198:201], v[80:83]
	v_mfma_f32_16x16x32_bf16 v[76:79], v[44:47], v[198:201], v[76:79]
	v_mfma_f32_16x16x32_bf16 v[36:39], v[36:39], v[206:209], v[72:75]
	v_mfma_f32_16x16x32_bf16 v[96:99], v[40:43], v[168:171], v[96:99]
	v_mfma_f32_16x16x32_bf16 v[92:95], v[48:51], v[168:171], v[92:95]
	v_mfma_f32_16x16x32_bf16 v[88:91], v[40:43], v[188:191], v[88:91]
	v_mfma_f32_16x16x32_bf16 v[84:87], v[48:51], v[188:191], v[84:87]
	v_mfma_f32_16x16x32_bf16 v[80:83], v[40:43], v[202:205], v[80:83]
	v_mfma_f32_16x16x32_bf16 v[76:79], v[48:51], v[202:205], v[76:79]
	v_mfma_f32_16x16x32_bf16 v[36:39], v[40:43], v[210:213], v[36:39]
	v_mfma_f32_16x16x32_bf16 v[40:43], v[44:47], v[206:209], v[68:71]
	v_mfma_f32_16x16x32_bf16 v[40:43], v[48:51], v[210:213], v[40:43]
	s_setprio 0
	s_setprio 1
	v_mfma_f32_16x16x32_bf16 v[28:31], v[52:55], v[164:167], v[28:31]
	v_mfma_f32_16x16x32_bf16 v[32:35], v[60:63], v[164:167], v[32:35]
	v_mfma_f32_16x16x32_bf16 v[20:23], v[52:55], v[184:187], v[20:23]
	v_mfma_f32_16x16x32_bf16 v[24:27], v[60:63], v[184:187], v[24:27]
	v_mfma_f32_16x16x32_bf16 v[16:19], v[52:55], v[198:201], v[16:19]
	v_mfma_f32_16x16x32_bf16 v[12:15], v[60:63], v[198:201], v[12:15]
	v_mfma_f32_16x16x32_bf16 v[8:11], v[52:55], v[206:209], v[8:11]
	v_mfma_f32_16x16x32_bf16 v[4:7], v[60:63], v[206:209], v[4:7]
	v_mfma_f32_16x16x32_bf16 v[28:31], v[56:59], v[168:171], v[28:31]
	v_mfma_f32_16x16x32_bf16 v[32:35], v[64:67], v[168:171], v[32:35]
	v_mfma_f32_16x16x32_bf16 v[20:23], v[56:59], v[188:191], v[20:23]
	v_mfma_f32_16x16x32_bf16 v[24:27], v[64:67], v[188:191], v[24:27]
	v_mfma_f32_16x16x32_bf16 v[16:19], v[56:59], v[202:205], v[16:19]
	v_mfma_f32_16x16x32_bf16 v[12:15], v[64:67], v[202:205], v[12:15]
	v_mfma_f32_16x16x32_bf16 v[8:11], v[56:59], v[210:213], v[8:11]
	v_mfma_f32_16x16x32_bf16 v[4:7], v[64:67], v[210:213], v[4:7]
	s_setprio 0
	s_barrier

; #define PG8_STAGE(bufoff, gbase, voff) do { _Pragma("unroll") for (int _i = 0; _i < 2; ++_i) \
;         __builtin_amdgcn_global_load_lds((const unsigned*)((const char*)(gbase) + (voff)[_i]), (PG8_LAS unsigned*)(lds + (bufoff) + ldsw + _i * 8192), 16, 0, 0); } while (0)
; #define PG8_LDA(dst, b, h) do { _Pragma("unroll") for (int m = 0; m < 4; ++m) _Pragma("unroll") for (int k = 0; k < 2; ++k) dst[m][k] = *(const PG8_LAS bf16x8*)(lds + PG8_SA(b, h) + aoff + m * 2048 + k * 1024); } while (0)
; #define PG8_LDB(dst, b, h) do { _Pragma("unroll") for (int n = 0; n < 2; ++n) _Pragma("unroll") for (int k = 0; k < 2; ++k) dst[n][k] = *(const PG8_LAS bf16x8*)(lds + PG8_SB(b, h) + boff + n * 2048 + k * 1024); } while (0)
; #define PG8_MMA(ai, bj, At, Bt) do { __builtin_amdgcn_s_setprio(1); _Pragma("unroll") for (int m = 0; m < 4; ++m) _Pragma("unroll") for (int n = 0; n < 2; ++n) _Pragma("unroll") for (int k = 0; k < 2; ++k) \
;         acc[ai][bj][m][n] = __builtin_amdgcn_mfma_f32_16x16x32_bf16(Bt[n][k], At[m][k], acc[ai][bj][m][n], 0, 0, 0); __builtin_amdgcn_s_setprio(0); } while (0)
; template <class Epi, class Sched, bool ALIGN_EPI = false, bool SP2 = false, bool ACHUNK = false>
; __device__ __forceinline__ void gemm_phase(PG8_LAS unsigned char* lds, const Gemm g, const Sched& S, const Epi& E) {
;     ...
;             if constexpr (SP2) {
;             PG8_LDB(B0, 0, 0); PG8_LDB(B1, 0, 1); PG8_SCHED; PG8_LDA(At, 0, 0); PG8_STAGE(PG8_SA(1, 1), a1 + hstepA, voffA);
;             PG8_WAIT_V(8); PG8_WAIT_L(0); PG8_BAR; PG8_MMA(0, 0, At, B0); PG8_MMA(0, 1, At, B1); PG8_BAR; PG8_SCHED;
;             PG8_LDA(At, 0, 1); PG8_STAGE(PG8_SB(0, 0), b2, voffB); PG8_STAGE(PG8_SB(0, 1), b2 + hstepB, voffB); PG8_STAGE(PG8_SA(0, 0), a2, voffA);
;             PG8_WAIT_V(8); PG8_WAIT_L(0); PG8_BAR; PG8_MMA(1, 0, At, B0); PG8_MMA(1, 1, At, B1); PG8_BAR; PG8_SCHED;
;             PG8_LDB(B0, 1, 0); PG8_LDB(B1, 1, 1); PG8_SCHED; PG8_LDA(At, 1, 0); PG8_STAGE(PG8_SA(0, 1), a2 + hstepA, voffA);
;             PG8_WAIT_V(8); PG8_WAIT_L(0); PG8_BAR; PG8_MMA(0, 0, At, B0); PG8_MMA(0, 1, At, B1); PG8_BAR; PG8_SCHED;
;             PG8_LDA(At, 1, 1); PG8_STAGE(PG8_SB(1, 0), b3, voffB); PG8_STAGE(PG8_SB(1, 1), b3 + hstepB, voffB); PG8_STAGE(PG8_SA(1, 0), a3, voffA);
;             PG8_WAIT_V(8); PG8_WAIT_L(0); PG8_BAR; PG8_MMA(1, 0, At, B0); PG8_MMA(1, 1, At, B1); PG8_BAR; PG8_SCHED;
.LBB0_375:
	s_andn2_b64 vcc, exec, s[34:35]
	s_cbranch_vccnz .LBB0_379
	s_add_u32 s4, s4, 0x80
	s_addc_u32 s5, s5, 0
	s_add_u32 s8, s6, 0x100
	s_addc_u32 s9, s7, 0
	s_mov_b32 s6, 0
	s_add_i32 s48, s6, 2
	s_add_u32 s49, s4, 0x80
	s_addc_u32 s7, s5, 0
	s_add_i32 s52, 0, 0x10000
	s_cmp_eq_u32 s27, s6
	s_cselect_b32 s7, s1, s7
	s_cselect_b32 s6, s0, s49
	v_add_u32_e32 v2, s52, v175
	s_cselect_b32 s51, s43, s9
	s_cselect_b32 s50, s42, s8
	s_cbranch_scc0 .Lnl_in_pe
	s_cmpk_lg_u32 s87, 0x100
	s_cbranch_scc1 .Lnl_in_pe
	s_cmp_eq_u32 s38, 0
	s_cbranch_scc1 .Lnl_in_pe
	v_mov_b32_e32 v134, 0
	v_mov_b32_e32 v138, 0
	v_mov_b32_e32 v132, 0
	v_mov_b32_e32 v136, 0
.Lnl_in_pe:
	s_add_i32 s49, 0, 0x14000
	s_waitcnt lgkmcnt(0)
	ds_read_b128 v[146:149], v2
	ds_read_b128 v[150:153], v2 offset:1024
	ds_read_b128 v[154:157], v2 offset:2048
	ds_read_b128 v[158:161], v2 offset:3072
	v_add_u32_e32 v2, s49, v175
	ds_read_b128 v[162:165], v2
	ds_read_b128 v[166:169], v2 offset:1024
	ds_read_b128 v[170:173], v2 offset:2048
	ds_read_b128 v[180:183], v2 offset:3072
	s_add_i32 m0, s20, 0xc000
	ds_read_b128 v[184:187], v179
	ds_read_b128 v[188:191], v179 offset:1024
	ds_read_b128 v[198:201], v179 offset:2048
	ds_read_b128 v[202:205], v179 offset:3072
	ds_read_b128 v[206:209], v179 offset:4096
	ds_read_b128 v[210:213], v179 offset:5120
	ds_read_b128 v[214:217], v179 offset:6144
	ds_read_b128 v[218:221], v179 offset:7168
	global_load_lds_dwordx4 v142, s[4:5]
	s_add_i32 m0, s20, 0xe000
	s_nop 0
	global_load_lds_dwordx4 v144, s[4:5]
	s_waitcnt vmcnt(8)
	s_waitcnt lgkmcnt(0)
	s_barrier
	s_setprio 1
	v_mfma_f32_16x16x32_bf16 v[124:127], v[146:149], v[184:187], 0
	v_mfma_f32_16x16x32_bf16 v[116:119], v[154:157], v[184:187], 0
	v_mfma_f32_16x16x32_bf16 v[108:111], v[146:149], v[198:201], 0
	v_mfma_f32_16x16x32_bf16 v[100:103], v[154:157], v[198:201], 0
	v_mfma_f32_16x16x32_bf16 v[92:95], v[146:149], v[206:209], 0
	v_mfma_f32_16x16x32_bf16 v[84:87], v[154:157], v[206:209], 0
	v_mfma_f32_16x16x32_bf16 v[76:79], v[146:149], v[214:217], 0
	v_mfma_f32_16x16x32_bf16 v[68:71], v[154:157], v[214:217], 0
	v_mfma_f32_16x16x32_bf16 v[124:127], v[150:153], v[188:191], v[124:127]
	v_mfma_f32_16x16x32_bf16 v[116:119], v[158:161], v[188:191], v[116:119]
	v_mfma_f32_16x16x32_bf16 v[108:111], v[150:153], v[202:205], v[108:111]
	v_mfma_f32_16x16x32_bf16 v[100:103], v[158:161], v[202:205], v[100:103]
	v_mfma_f32_16x16x32_bf16 v[92:95], v[150:153], v[210:213], v[92:95]
	v_mfma_f32_16x16x32_bf16 v[84:87], v[158:161], v[210:213], v[84:87]
	v_mfma_f32_16x16x32_bf16 v[76:79], v[150:153], v[218:221], v[76:79]
	v_mfma_f32_16x16x32_bf16 v[68:71], v[158:161], v[218:221], v[68:71]
	s_setprio 0
	s_setprio 1
	v_mfma_f32_16x16x32_bf16 v[128:131], v[162:165], v[184:187], 0
	v_mfma_f32_16x16x32_bf16 v[120:123], v[170:173], v[184:187], 0
	v_mfma_f32_16x16x32_bf16 v[112:115], v[162:165], v[198:201], 0
	v_mfma_f32_16x16x32_bf16 v[104:107], v[170:173], v[198:201], 0
	v_mfma_f32_16x16x32_bf16 v[96:99], v[162:165], v[206:209], 0
	v_mfma_f32_16x16x32_bf16 v[88:91], v[170:173], v[206:209], 0
	v_mfma_f32_16x16x32_bf16 v[80:83], v[162:165], v[214:217], 0
	v_mfma_f32_16x16x32_bf16 v[72:75], v[170:173], v[214:217], 0
	v_mfma_f32_16x16x32_bf16 v[128:131], v[166:169], v[188:191], v[128:131]
	v_mfma_f32_16x16x32_bf16 v[120:123], v[180:183], v[188:191], v[120:123]
	v_mfma_f32_16x16x32_bf16 v[112:115], v[166:169], v[202:205], v[112:115]
	v_mfma_f32_16x16x32_bf16 v[104:107], v[180:183], v[202:205], v[104:107]
	v_mfma_f32_16x16x32_bf16 v[96:99], v[166:169], v[210:213], v[96:99]
	v_mfma_f32_16x16x32_bf16 v[88:91], v[180:183], v[210:213], v[88:91]
	v_mfma_f32_16x16x32_bf16 v[80:83], v[166:169], v[218:221], v[80:83]
	v_mfma_f32_16x16x32_bf16 v[72:75], v[180:183], v[218:221], v[72:75]
	s_setprio 0
	s_barrier
	s_add_i32 s52, s52, s13
	s_mov_b32 m0, s52
	ds_read_b128 v[184:187], v179 offset:16384
	ds_read_b128 v[188:191], v179 offset:17408
	ds_read_b128 v[198:201], v179 offset:18432
	ds_read_b128 v[202:205], v179 offset:19456
	ds_read_b128 v[206:209], v179 offset:20480
	ds_read_b128 v[210:213], v179 offset:21504
	ds_read_b128 v[214:217], v179 offset:22528
	ds_read_b128 v[218:221], v179 offset:23552
	global_load_lds_dwordx4 v134, s[50:51]
	s_add_i32 m0, s52, 0x2000
	s_add_i32 s49, s49, s13
	global_load_lds_dwordx4 v138, s[50:51]
	s_add_u32 s50, s50, s18
	s_addc_u32 s51, s51, s19
	s_mov_b64 vcc, s[50:51]
	s_sub_u32 s98, s50, s18
	s_subb_u32 s99, s51, s19
	s_mov_b32 m0, s49
	s_nop 0
	global_load_lds_dwordx4 v134, s[50:51]
	s_add_i32 m0, s49, 0x2000
	s_nop 0
	global_load_lds_dwordx4 v138, s[50:51]
	s_mov_b32 m0, s20
	s_nop 0
	global_load_lds_dwordx4 v132, s[6:7]
	s_mov_b32 m0, s21
	s_nop 0
	global_load_lds_dwordx4 v136, s[6:7]
	s_waitcnt vmcnt(8)
	s_waitcnt lgkmcnt(0)
	s_barrier
	s_setprio 1
	v_mfma_f32_16x16x32_bf16 v[60:63], v[146:149], v[184:187], 0
	v_mfma_f32_16x16x32_bf16 v[52:55], v[154:157], v[184:187], 0
	v_mfma_f32_16x16x32_bf16 v[44:47], v[146:149], v[198:201], 0
	v_mfma_f32_16x16x32_bf16 v[36:39], v[154:157], v[198:201], 0
	v_mfma_f32_16x16x32_bf16 v[28:31], v[146:149], v[206:209], 0
	v_mfma_f32_16x16x32_bf16 v[20:23], v[154:157], v[206:209], 0
	v_mfma_f32_16x16x32_bf16 v[12:15], v[146:149], v[214:217], 0
	v_mfma_f32_16x16x32_bf16 v[4:7], v[154:157], v[214:217], 0
	v_mfma_f32_16x16x32_bf16 v[60:63], v[150:153], v[188:191], v[60:63]
	v_mfma_f32_16x16x32_bf16 v[52:55], v[158:161], v[188:191], v[52:55]
	v_mfma_f32_16x16x32_bf16 v[44:47], v[150:153], v[202:205], v[44:47]
	v_mfma_f32_16x16x32_bf16 v[36:39], v[158:161], v[202:205], v[36:39]
	v_mfma_f32_16x16x32_bf16 v[28:31], v[150:153], v[210:213], v[28:31]
	v_mfma_f32_16x16x32_bf16 v[20:23], v[158:161], v[210:213], v[20:23]
	v_mfma_f32_16x16x32_bf16 v[12:15], v[150:153], v[218:221], v[12:15]
	v_mfma_f32_16x16x32_bf16 v[4:7], v[158:161], v[218:221], v[4:7]
	s_setprio 0
	s_setprio 1
	v_mfma_f32_16x16x32_bf16 v[64:67], v[162:165], v[184:187], 0
	v_mfma_f32_16x16x32_bf16 v[56:59], v[170:173], v[184:187], 0
	v_mfma_f32_16x16x32_bf16 v[48:51], v[162:165], v[198:201], 0
	v_mfma_f32_16x16x32_bf16 v[40:43], v[170:173], v[198:201], 0
	v_mfma_f32_16x16x32_bf16 v[32:35], v[162:165], v[206:209], 0
	v_mfma_f32_16x16x32_bf16 v[24:27], v[170:173], v[206:209], 0
	v_mfma_f32_16x16x32_bf16 v[16:19], v[162:165], v[214:217], 0
	v_mfma_f32_16x16x32_bf16 v[8:11], v[170:173], v[214:217], 0
	v_mfma_f32_16x16x32_bf16 v[64:67], v[166:169], v[188:191], v[64:67]
	v_mfma_f32_16x16x32_bf16 v[56:59], v[180:183], v[188:191], v[56:59]
	v_mfma_f32_16x16x32_bf16 v[48:51], v[166:169], v[202:205], v[48:51]
	v_mfma_f32_16x16x32_bf16 v[40:43], v[180:183], v[202:205], v[40:43]
	v_mfma_f32_16x16x32_bf16 v[32:35], v[166:169], v[210:213], v[32:35]
	v_mfma_f32_16x16x32_bf16 v[24:27], v[180:183], v[210:213], v[24:27]
	v_mfma_f32_16x16x32_bf16 v[16:19], v[166:169], v[218:221], v[16:19]
	v_mfma_f32_16x16x32_bf16 v[8:11], v[180:183], v[218:221], v[8:11]
	s_setprio 0
	s_barrier
	s_branch .Lpe_join_377
	.p2align	6
; #define PG8_STAGE(bufoff, gbase, voff) do { _Pragma("unroll") for (int _i = 0; _i < 2; ++_i) \
;         __builtin_amdgcn_global_load_lds((const unsigned*)((const char*)(gbase) + (voff)[_i]), (PG8_LAS unsigned*)(lds + (bufoff) + ldsw + _i * 8192), 16, 0, 0); } while (0)
; #define PG8_LDA(dst, b, h) do { _Pragma("unroll") for (int m = 0; m < 4; ++m) _Pragma("unroll") for (int k = 0; k < 2; ++k) dst[m][k] = *(const PG8_LAS bf16x8*)(lds + PG8_SA(b, h) + aoff + m * 2048 + k * 1024); } while (0)
; #define PG8_LDB(dst, b, h) do { _Pragma("unroll") for (int n = 0; n < 2; ++n) _Pragma("unroll") for (int k = 0; k < 2; ++k) dst[n][k] = *(const PG8_LAS bf16x8*)(lds + PG8_SB(b, h) + boff + n * 2048 + k * 1024); } while (0)
; #define PG8_MMA(ai, bj, At, Bt) do { __builtin_amdgcn_s_setprio(1); _Pragma("unroll") for (int m = 0; m < 4; ++m) _Pragma("unroll") for (int n = 0; n < 2; ++n) _Pragma("unroll") for (int k = 0; k < 2; ++k) \
;         acc[ai][bj][m][n] = __builtin_amdgcn_mfma_f32_16x16x32_bf16(Bt[n][k], At[m][k], acc[ai][bj][m][n], 0, 0, 0); __builtin_amdgcn_s_setprio(0); } while (0)
; template <class Epi, class Sched, bool ALIGN_EPI = false, bool SP2 = false, bool ACHUNK = false>
; __device__ __forceinline__ void gemm_phase(PG8_LAS unsigned char* lds, const Gemm g, const Sched& S, const Epi& E) {
;     ...
;             if constexpr (SP2) {
;             PG8_LDB(B0, 0, 0); PG8_LDB(B1, 0, 1); PG8_SCHED; PG8_LDA(At, 0, 0); PG8_STAGE(PG8_SA(1, 1), a1 + hstepA, voffA);
;             PG8_WAIT_V(8); PG8_WAIT_L(0); PG8_BAR; PG8_MMA(0, 0, At, B0); PG8_MMA(0, 1, At, B1); PG8_BAR; PG8_SCHED;
;             PG8_LDA(At, 0, 1); PG8_STAGE(PG8_SB(0, 0), b2, voffB); PG8_STAGE(PG8_SB(0, 1), b2 + hstepB, voffB); PG8_STAGE(PG8_SA(0, 0), a2, voffA);
;             PG8_WAIT_V(8); PG8_WAIT_L(0); PG8_BAR; PG8_MMA(1, 0, At, B0); PG8_MMA(1, 1, At, B1); PG8_BAR; PG8_SCHED;
;             PG8_LDB(B0, 1, 0); PG8_LDB(B1, 1, 1); PG8_SCHED; PG8_LDA(At, 1, 0); PG8_STAGE(PG8_SA(0, 1), a2 + hstepA, voffA);
;             PG8_WAIT_V(8); PG8_WAIT_L(0); PG8_BAR; PG8_MMA(0, 0, At, B0); PG8_MMA(0, 1, At, B1); PG8_BAR; PG8_SCHED;
;             PG8_LDA(At, 1, 1); PG8_STAGE(PG8_SB(1, 0), b3, voffB); PG8_STAGE(PG8_SB(1, 1), b3 + hstepB, voffB); PG8_STAGE(PG8_SA(1, 0), a3, voffA);
;             PG8_WAIT_V(8); PG8_WAIT_L(0); PG8_BAR; PG8_MMA(1, 0, At, B0); PG8_MMA(1, 1, At, B1); PG8_BAR; PG8_SCHED;
.LBB0_377:
	s_add_i32 s48, s6, 2
	s_add_u32 s49, s4, 0x80
	s_addc_u32 s7, s5, 0
	s_add_i32 s52, 0, 0x10000
	s_cmp_eq_u32 s27, s6
	s_cselect_b32 s7, s1, s7
	s_cselect_b32 s6, s0, s49
	v_add_u32_e32 v2, s52, v175
	s_cselect_b32 s51, s43, s9
	s_cselect_b32 s50, s42, s8
	s_cbranch_scc0 .Lnl_in
	s_cmpk_lg_u32 s87, 0x100
	s_cbranch_scc1 .Lnl_in
	s_cmp_eq_u32 s38, 0
	s_cbranch_scc1 .Lnl_in
	v_mov_b32_e32 v134, 0
	v_mov_b32_e32 v138, 0
	v_mov_b32_e32 v132, 0
	v_mov_b32_e32 v136, 0
.Lnl_in:
	s_add_i32 s49, 0, 0x14000
	s_waitcnt lgkmcnt(0)
	ds_read_b128 v[146:149], v2
	ds_read_b128 v[150:153], v2 offset:1024
	ds_read_b128 v[154:157], v2 offset:2048
	ds_read_b128 v[158:161], v2 offset:3072
	v_add_u32_e32 v2, s49, v175
	ds_read_b128 v[162:165], v2
	ds_read_b128 v[166:169], v2 offset:1024
	ds_read_b128 v[170:173], v2 offset:2048
	ds_read_b128 v[180:183], v2 offset:3072
	s_add_i32 m0, s20, 0xc000
	ds_read_b128 v[184:187], v179
	ds_read_b128 v[188:191], v179 offset:1024
	ds_read_b128 v[198:201], v179 offset:2048
	ds_read_b128 v[202:205], v179 offset:3072
	ds_read_b128 v[206:209], v179 offset:4096
	ds_read_b128 v[210:213], v179 offset:5120
	ds_read_b128 v[214:217], v179 offset:6144
	ds_read_b128 v[218:221], v179 offset:7168
	global_load_lds_dwordx4 v142, s[4:5]
	s_add_i32 m0, s20, 0xe000
	s_nop 0
	global_load_lds_dwordx4 v144, s[4:5]
	s_waitcnt vmcnt(8)
	s_waitcnt lgkmcnt(0)
	s_barrier
	s_setprio 1
	v_mfma_f32_16x16x32_bf16 v[124:127], v[146:149], v[184:187], v[124:127]
	v_mfma_f32_16x16x32_bf16 v[116:119], v[154:157], v[184:187], v[116:119]
	v_mfma_f32_16x16x32_bf16 v[108:111], v[146:149], v[198:201], v[108:111]
	v_mfma_f32_16x16x32_bf16 v[100:103], v[154:157], v[198:201], v[100:103]
	v_mfma_f32_16x16x32_bf16 v[92:95], v[146:149], v[206:209], v[92:95]
	v_mfma_f32_16x16x32_bf16 v[84:87], v[154:157], v[206:209], v[84:87]
	v_mfma_f32_16x16x32_bf16 v[76:79], v[146:149], v[214:217], v[76:79]
	v_mfma_f32_16x16x32_bf16 v[68:71], v[154:157], v[214:217], v[68:71]
	v_mfma_f32_16x16x32_bf16 v[124:127], v[150:153], v[188:191], v[124:127]
	v_mfma_f32_16x16x32_bf16 v[116:119], v[158:161], v[188:191], v[116:119]
	v_mfma_f32_16x16x32_bf16 v[108:111], v[150:153], v[202:205], v[108:111]
	v_mfma_f32_16x16x32_bf16 v[100:103], v[158:161], v[202:205], v[100:103]
	v_mfma_f32_16x16x32_bf16 v[92:95], v[150:153], v[210:213], v[92:95]
	v_mfma_f32_16x16x32_bf16 v[84:87], v[158:161], v[210:213], v[84:87]
	v_mfma_f32_16x16x32_bf16 v[76:79], v[150:153], v[218:221], v[76:79]
	v_mfma_f32_16x16x32_bf16 v[68:71], v[158:161], v[218:221], v[68:71]
	s_setprio 0
	s_setprio 1
	v_mfma_f32_16x16x32_bf16 v[128:131], v[162:165], v[184:187], v[128:131]
	v_mfma_f32_16x16x32_bf16 v[120:123], v[170:173], v[184:187], v[120:123]
	v_mfma_f32_16x16x32_bf16 v[112:115], v[162:165], v[198:201], v[112:115]
	v_mfma_f32_16x16x32_bf16 v[104:107], v[170:173], v[198:201], v[104:107]
	v_mfma_f32_16x16x32_bf16 v[96:99], v[162:165], v[206:209], v[96:99]
	v_mfma_f32_16x16x32_bf16 v[88:91], v[170:173], v[206:209], v[88:91]
	v_mfma_f32_16x16x32_bf16 v[80:83], v[162:165], v[214:217], v[80:83]
	v_mfma_f32_16x16x32_bf16 v[72:75], v[170:173], v[214:217], v[72:75]
	v_mfma_f32_16x16x32_bf16 v[128:131], v[166:169], v[188:191], v[128:131]
	v_mfma_f32_16x16x32_bf16 v[120:123], v[180:183], v[188:191], v[120:123]
	v_mfma_f32_16x16x32_bf16 v[112:115], v[166:169], v[202:205], v[112:115]
	v_mfma_f32_16x16x32_bf16 v[104:107], v[180:183], v[202:205], v[104:107]
	v_mfma_f32_16x16x32_bf16 v[96:99], v[166:169], v[210:213], v[96:99]
	v_mfma_f32_16x16x32_bf16 v[88:91], v[180:183], v[210:213], v[88:91]
	v_mfma_f32_16x16x32_bf16 v[80:83], v[166:169], v[218:221], v[80:83]
	v_mfma_f32_16x16x32_bf16 v[72:75], v[180:183], v[218:221], v[72:75]
	s_setprio 0
	s_barrier
	s_add_i32 s52, s52, s13
	s_mov_b32 m0, s52
	ds_read_b128 v[184:187], v179 offset:16384
	ds_read_b128 v[188:191], v179 offset:17408
	ds_read_b128 v[198:201], v179 offset:18432
	ds_read_b128 v[202:205], v179 offset:19456
	ds_read_b128 v[206:209], v179 offset:20480
	ds_read_b128 v[210:213], v179 offset:21504
	ds_read_b128 v[214:217], v179 offset:22528
	ds_read_b128 v[218:221], v179 offset:23552
	global_load_lds_dwordx4 v134, s[50:51]
	s_add_i32 m0, s52, 0x2000
	s_add_i32 s49, s49, s13
	global_load_lds_dwordx4 v138, s[50:51]
	s_add_u32 s50, s50, s18
	s_addc_u32 s51, s51, s19
	s_mov_b64 vcc, s[50:51]
	s_sub_u32 s98, s50, s18
	s_subb_u32 s99, s51, s19
	s_mov_b32 m0, s49
	s_nop 0
	global_load_lds_dwordx4 v134, s[50:51]
	s_add_i32 m0, s49, 0x2000
	s_nop 0
	global_load_lds_dwordx4 v138, s[50:51]
	s_mov_b32 m0, s20
	s_nop 0
	global_load_lds_dwordx4 v132, s[6:7]
	s_mov_b32 m0, s21
	s_nop 0
	global_load_lds_dwordx4 v136, s[6:7]
	s_waitcnt vmcnt(8)
	s_waitcnt lgkmcnt(0)
	s_barrier
	s_setprio 1
	v_mfma_f32_16x16x32_bf16 v[60:63], v[146:149], v[184:187], v[60:63]
	v_mfma_f32_16x16x32_bf16 v[52:55], v[154:157], v[184:187], v[52:55]
	v_mfma_f32_16x16x32_bf16 v[44:47], v[146:149], v[198:201], v[44:47]
	v_mfma_f32_16x16x32_bf16 v[36:39], v[154:157], v[198:201], v[36:39]
	v_mfma_f32_16x16x32_bf16 v[28:31], v[146:149], v[206:209], v[28:31]
	v_mfma_f32_16x16x32_bf16 v[20:23], v[154:157], v[206:209], v[20:23]
	v_mfma_f32_16x16x32_bf16 v[12:15], v[146:149], v[214:217], v[12:15]
	v_mfma_f32_16x16x32_bf16 v[4:7], v[154:157], v[214:217], v[4:7]
	v_mfma_f32_16x16x32_bf16 v[60:63], v[150:153], v[188:191], v[60:63]
	v_mfma_f32_16x16x32_bf16 v[52:55], v[158:161], v[188:191], v[52:55]
	v_mfma_f32_16x16x32_bf16 v[44:47], v[150:153], v[202:205], v[44:47]
	v_mfma_f32_16x16x32_bf16 v[36:39], v[158:161], v[202:205], v[36:39]
	v_mfma_f32_16x16x32_bf16 v[28:31], v[150:153], v[210:213], v[28:31]
	v_mfma_f32_16x16x32_bf16 v[20:23], v[158:161], v[210:213], v[20:23]
	v_mfma_f32_16x16x32_bf16 v[12:15], v[150:153], v[218:221], v[12:15]
	v_mfma_f32_16x16x32_bf16 v[4:7], v[158:161], v[218:221], v[4:7]
	s_setprio 0
	s_setprio 1
	v_mfma_f32_16x16x32_bf16 v[64:67], v[162:165], v[184:187], v[64:67]
	v_mfma_f32_16x16x32_bf16 v[56:59], v[170:173], v[184:187], v[56:59]
	v_mfma_f32_16x16x32_bf16 v[48:51], v[162:165], v[198:201], v[48:51]
	v_mfma_f32_16x16x32_bf16 v[40:43], v[170:173], v[198:201], v[40:43]
	v_mfma_f32_16x16x32_bf16 v[32:35], v[162:165], v[206:209], v[32:35]
	v_mfma_f32_16x16x32_bf16 v[24:27], v[170:173], v[206:209], v[24:27]
	v_mfma_f32_16x16x32_bf16 v[16:19], v[162:165], v[214:217], v[16:19]
	v_mfma_f32_16x16x32_bf16 v[8:11], v[170:173], v[214:217], v[8:11]
	v_mfma_f32_16x16x32_bf16 v[64:67], v[166:169], v[188:191], v[64:67]
	v_mfma_f32_16x16x32_bf16 v[56:59], v[180:183], v[188:191], v[56:59]
	v_mfma_f32_16x16x32_bf16 v[48:51], v[166:169], v[202:205], v[48:51]
	v_mfma_f32_16x16x32_bf16 v[40:43], v[180:183], v[202:205], v[40:43]
	v_mfma_f32_16x16x32_bf16 v[32:35], v[166:169], v[210:213], v[32:35]
	v_mfma_f32_16x16x32_bf16 v[24:27], v[180:183], v[210:213], v[24:27]
	v_mfma_f32_16x16x32_bf16 v[16:19], v[166:169], v[218:221], v[16:19]
	v_mfma_f32_16x16x32_bf16 v[8:11], v[180:183], v[218:221], v[8:11]
	s_setprio 0
	s_barrier
